# conv1d fast path extended to the context rows (stride 2560, T=256)
# speedup vs baseline: 1.0188x; 1.0188x over previous
.Lc1_top:
	v_readfirstlane_b32 s84, v43
	v_readfirstlane_b32 s85, v104
	v_readfirstlane_b32 s88, v36
	v_readfirstlane_b32 s94, v56
	v_readfirstlane_b32 s95, v57
	v_lshlrev_b32_e32 v252, 1, v36
	s_nop 1
	s_lshl_b32 s88, s88, 1
	v_subrev_u32_e32 v252, s88, v252
	s_add_u32 s91, s84, 8
	s_cmp_gt_u32 s91, s85
	s_cbranch_scc1 .LBB0_360
	s_cmp_ge_u32 s84, 0x10000
	s_cbranch_scc1 .Lc1_ctx
	s_cmp_gt_u32 s91, 0x10000
	s_cbranch_scc1 .LBB0_360
	s_and_b32 s91, s84, 0x1fff
	s_cmp_lt_u32 s91, 2
	s_cbranch_scc1 .LBB0_360
	s_cmp_gt_u32 s91, 0x1ff7
	s_cbranch_scc1 .LBB0_360
	v_readfirstlane_b32 s86, v54
	v_readfirstlane_b32 s87, v55
	s_nop 1
	s_add_u32 s86, s86, s88
	s_addc_u32 s87, s87, 0
	s_sub_u32 s92, s86, 0x6800
	s_subb_u32 s93, s87, 0
	global_load_dwordx2 v[208:209], v252, s[92:93]
	s_add_u32 s92, s92, 0x3400
	s_addc_u32 s93, s93, 0
	global_load_dwordx2 v[212:213], v252, s[92:93]
	s_add_u32 s92, s92, 0x3400
	s_addc_u32 s93, s93, 0
	global_load_dwordx2 v[216:217], v252, s[92:93]
	s_add_u32 s92, s92, 0x3400
	s_addc_u32 s93, s93, 0
	global_load_dwordx2 v[220:221], v252, s[92:93]
	s_add_u32 s92, s92, 0x3400
	s_addc_u32 s93, s93, 0
	global_load_dwordx2 v[224:225], v252, s[92:93]
	s_add_u32 s92, s92, 0x3400
	s_addc_u32 s93, s93, 0
	global_load_dwordx2 v[228:229], v252, s[92:93]
	s_add_u32 s92, s92, 0x3400
	s_addc_u32 s93, s93, 0
	global_load_dwordx2 v[232:233], v252, s[92:93]
	s_add_u32 s92, s92, 0x3400
	s_addc_u32 s93, s93, 0
	global_load_dwordx2 v[236:237], v252, s[92:93]
	s_add_u32 s92, s92, 0x3400
	s_addc_u32 s93, s93, 0
	global_load_dwordx2 v[240:241], v252, s[92:93]
	s_add_u32 s92, s92, 0x3400
	s_addc_u32 s93, s93, 0
	global_load_dwordx2 v[244:245], v252, s[92:93]
	s_add_u32 s92, s92, 0x3400
	s_addc_u32 s93, s93, 0
	global_load_dwordx2 v[248:249], v252, s[92:93]
	s_waitcnt vmcnt(0)
	v_lshlrev_b32_e32 v210, 16, v209
	v_and_b32_e32 v211, 0xffff0000, v209
	v_and_b32_e32 v209, 0xffff0000, v208
	v_lshlrev_b32_e32 v208, 16, v208
	v_lshlrev_b32_e32 v214, 16, v213
	v_and_b32_e32 v215, 0xffff0000, v213
	v_and_b32_e32 v213, 0xffff0000, v212
	v_lshlrev_b32_e32 v212, 16, v212
	v_lshlrev_b32_e32 v218, 16, v217
	v_and_b32_e32 v219, 0xffff0000, v217
	v_and_b32_e32 v217, 0xffff0000, v216
	v_lshlrev_b32_e32 v216, 16, v216
	v_lshlrev_b32_e32 v222, 16, v221
	v_and_b32_e32 v223, 0xffff0000, v221
	v_and_b32_e32 v221, 0xffff0000, v220
	v_lshlrev_b32_e32 v220, 16, v220
	v_lshlrev_b32_e32 v226, 16, v225
	v_and_b32_e32 v227, 0xffff0000, v225
	v_and_b32_e32 v225, 0xffff0000, v224
	v_lshlrev_b32_e32 v224, 16, v224
	v_lshlrev_b32_e32 v230, 16, v229
	v_and_b32_e32 v231, 0xffff0000, v229
	v_and_b32_e32 v229, 0xffff0000, v228
	v_lshlrev_b32_e32 v228, 16, v228
	v_lshlrev_b32_e32 v234, 16, v233
	v_and_b32_e32 v235, 0xffff0000, v233
	v_and_b32_e32 v233, 0xffff0000, v232
	v_lshlrev_b32_e32 v232, 16, v232
	v_lshlrev_b32_e32 v238, 16, v237
	v_and_b32_e32 v239, 0xffff0000, v237
	v_and_b32_e32 v237, 0xffff0000, v236
	v_lshlrev_b32_e32 v236, 16, v236
	v_lshlrev_b32_e32 v242, 16, v241
	v_and_b32_e32 v243, 0xffff0000, v241
	v_and_b32_e32 v241, 0xffff0000, v240
	v_lshlrev_b32_e32 v240, 16, v240
	v_lshlrev_b32_e32 v246, 16, v245
	v_and_b32_e32 v247, 0xffff0000, v245
	v_and_b32_e32 v245, 0xffff0000, v244
	v_lshlrev_b32_e32 v244, 16, v244
	v_lshlrev_b32_e32 v250, 16, v249
	v_and_b32_e32 v251, 0xffff0000, v249
	v_and_b32_e32 v249, 0xffff0000, v248
	v_lshlrev_b32_e32 v248, 16, v248
	v_pk_fma_f32 v[208:209], v[0:1], v[208:209], v[16:17]
	v_pk_fma_f32 v[210:211], v[2:3], v[210:211], v[18:19]
	v_pk_fma_f32 v[208:209], v[4:5], v[212:213], v[208:209]
	v_pk_fma_f32 v[210:211], v[6:7], v[214:215], v[210:211]
	v_pk_fma_f32 v[208:209], v[8:9], v[216:217], v[208:209]
	v_pk_fma_f32 v[210:211], v[10:11], v[218:219], v[210:211]
	v_pk_fma_f32 v[208:209], v[12:13], v[220:221], v[208:209]
	v_pk_fma_f32 v[210:211], v[14:15], v[222:223], v[210:211]
	v_cvt_pk_bf16_f32 v208, v208, v209
	v_cvt_pk_bf16_f32 v209, v210, v211
	global_store_dwordx2 v252, v[208:209], s[94:95]
	s_add_u32 s94, s94, 0xa00
	s_addc_u32 s95, s95, 0
	v_pk_fma_f32 v[212:213], v[0:1], v[212:213], v[16:17]
	v_pk_fma_f32 v[214:215], v[2:3], v[214:215], v[18:19]
	v_pk_fma_f32 v[212:213], v[4:5], v[216:217], v[212:213]
	v_pk_fma_f32 v[214:215], v[6:7], v[218:219], v[214:215]
	v_pk_fma_f32 v[212:213], v[8:9], v[220:221], v[212:213]
	v_pk_fma_f32 v[214:215], v[10:11], v[222:223], v[214:215]
	v_pk_fma_f32 v[212:213], v[12:13], v[224:225], v[212:213]
	v_pk_fma_f32 v[214:215], v[14:15], v[226:227], v[214:215]
	v_cvt_pk_bf16_f32 v212, v212, v213
	v_cvt_pk_bf16_f32 v213, v214, v215
	global_store_dwordx2 v252, v[212:213], s[94:95]
	s_add_u32 s94, s94, 0xa00
	s_addc_u32 s95, s95, 0
	v_pk_fma_f32 v[216:217], v[0:1], v[216:217], v[16:17]
	v_pk_fma_f32 v[218:219], v[2:3], v[218:219], v[18:19]
	v_pk_fma_f32 v[216:217], v[4:5], v[220:221], v[216:217]
	v_pk_fma_f32 v[218:219], v[6:7], v[222:223], v[218:219]
	v_pk_fma_f32 v[216:217], v[8:9], v[224:225], v[216:217]
	v_pk_fma_f32 v[218:219], v[10:11], v[226:227], v[218:219]
	v_pk_fma_f32 v[216:217], v[12:13], v[228:229], v[216:217]
	v_pk_fma_f32 v[218:219], v[14:15], v[230:231], v[218:219]
	v_cvt_pk_bf16_f32 v216, v216, v217
	v_cvt_pk_bf16_f32 v217, v218, v219
	global_store_dwordx2 v252, v[216:217], s[94:95]
	s_add_u32 s94, s94, 0xa00
	s_addc_u32 s95, s95, 0
	v_pk_fma_f32 v[220:221], v[0:1], v[220:221], v[16:17]
	v_pk_fma_f32 v[222:223], v[2:3], v[222:223], v[18:19]
	v_pk_fma_f32 v[220:221], v[4:5], v[224:225], v[220:221]
	v_pk_fma_f32 v[222:223], v[6:7], v[226:227], v[222:223]
	v_pk_fma_f32 v[220:221], v[8:9], v[228:229], v[220:221]
	v_pk_fma_f32 v[222:223], v[10:11], v[230:231], v[222:223]
	v_pk_fma_f32 v[220:221], v[12:13], v[232:233], v[220:221]
	v_pk_fma_f32 v[222:223], v[14:15], v[234:235], v[222:223]
	v_cvt_pk_bf16_f32 v220, v220, v221
	v_cvt_pk_bf16_f32 v221, v222, v223
	global_store_dwordx2 v252, v[220:221], s[94:95]
	s_add_u32 s94, s94, 0xa00
	s_addc_u32 s95, s95, 0
	v_pk_fma_f32 v[224:225], v[0:1], v[224:225], v[16:17]
	v_pk_fma_f32 v[226:227], v[2:3], v[226:227], v[18:19]
	v_pk_fma_f32 v[224:225], v[4:5], v[228:229], v[224:225]
	v_pk_fma_f32 v[226:227], v[6:7], v[230:231], v[226:227]
	v_pk_fma_f32 v[224:225], v[8:9], v[232:233], v[224:225]
	v_pk_fma_f32 v[226:227], v[10:11], v[234:235], v[226:227]
	v_pk_fma_f32 v[224:225], v[12:13], v[236:237], v[224:225]
	v_pk_fma_f32 v[226:227], v[14:15], v[238:239], v[226:227]
	v_cvt_pk_bf16_f32 v224, v224, v225
	v_cvt_pk_bf16_f32 v225, v226, v227
	global_store_dwordx2 v252, v[224:225], s[94:95]
	s_add_u32 s94, s94, 0xa00
	s_addc_u32 s95, s95, 0
	v_pk_fma_f32 v[228:229], v[0:1], v[228:229], v[16:17]
	v_pk_fma_f32 v[230:231], v[2:3], v[230:231], v[18:19]
	v_pk_fma_f32 v[228:229], v[4:5], v[232:233], v[228:229]
	v_pk_fma_f32 v[230:231], v[6:7], v[234:235], v[230:231]
	v_pk_fma_f32 v[228:229], v[8:9], v[236:237], v[228:229]
	v_pk_fma_f32 v[230:231], v[10:11], v[238:239], v[230:231]
	v_pk_fma_f32 v[228:229], v[12:13], v[240:241], v[228:229]
	v_pk_fma_f32 v[230:231], v[14:15], v[242:243], v[230:231]
	v_cvt_pk_bf16_f32 v228, v228, v229
	v_cvt_pk_bf16_f32 v229, v230, v231
	global_store_dwordx2 v252, v[228:229], s[94:95]
	s_add_u32 s94, s94, 0xa00
	s_addc_u32 s95, s95, 0
	v_pk_fma_f32 v[232:233], v[0:1], v[232:233], v[16:17]
	v_pk_fma_f32 v[234:235], v[2:3], v[234:235], v[18:19]
	v_pk_fma_f32 v[232:233], v[4:5], v[236:237], v[232:233]
	v_pk_fma_f32 v[234:235], v[6:7], v[238:239], v[234:235]
	v_pk_fma_f32 v[232:233], v[8:9], v[240:241], v[232:233]
	v_pk_fma_f32 v[234:235], v[10:11], v[242:243], v[234:235]
	v_pk_fma_f32 v[232:233], v[12:13], v[244:245], v[232:233]
	v_pk_fma_f32 v[234:235], v[14:15], v[246:247], v[234:235]
	v_cvt_pk_bf16_f32 v232, v232, v233
	v_cvt_pk_bf16_f32 v233, v234, v235
	global_store_dwordx2 v252, v[232:233], s[94:95]
	s_add_u32 s94, s94, 0xa00
	s_addc_u32 s95, s95, 0
	v_pk_fma_f32 v[236:237], v[0:1], v[236:237], v[16:17]
	v_pk_fma_f32 v[238:239], v[2:3], v[238:239], v[18:19]
	v_pk_fma_f32 v[236:237], v[4:5], v[240:241], v[236:237]
	v_pk_fma_f32 v[238:239], v[6:7], v[242:243], v[238:239]
	v_pk_fma_f32 v[236:237], v[8:9], v[244:245], v[236:237]
	v_pk_fma_f32 v[238:239], v[10:11], v[246:247], v[238:239]
	v_pk_fma_f32 v[236:237], v[12:13], v[248:249], v[236:237]
	v_pk_fma_f32 v[238:239], v[14:15], v[250:251], v[238:239]
	v_cvt_pk_bf16_f32 v236, v236, v237
	v_cvt_pk_bf16_f32 v237, v238, v239
	global_store_dwordx2 v252, v[236:237], s[94:95]
	s_mov_b32 s66, 0x1a000
	s_mov_b32 s67, 0
	s_mov_b32 s68, 0x5000
	s_mov_b32 s69, 0
	v_add_u32_e32 v43, 8, v43
	v_lshl_add_u64 v[54:55], v[54:55], 0, s[66:67]
	v_lshl_add_u64 v[56:57], v[56:57], 0, s[68:69]
	s_add_u32 s84, s84, 8
	s_cmp_lt_u32 s84, s85
	s_cbranch_scc1 .Lc1_top
	s_branch .LBB0_344
.Lc1_ctx:
	s_and_b32 s91, s84, 0xff
	s_cmp_lt_u32 s91, 2
	s_cbranch_scc1 .LBB0_360
	s_cmp_gt_u32 s91, 0xf7
	s_cbranch_scc1 .LBB0_360
	s_sub_u32 s91, s84, 0x10002
	s_mul_i32 s91, s91, 0xa00
	s_add_u32 s92, s46, s91
	s_addc_u32 s93, s47, 0
	s_add_u32 s92, s92, s88
	s_addc_u32 s93, s93, 0
	global_load_dwordx2 v[208:209], v252, s[92:93]
	s_add_u32 s92, s92, 0xa00
	s_addc_u32 s93, s93, 0
	global_load_dwordx2 v[212:213], v252, s[92:93]
	s_add_u32 s92, s92, 0xa00
	s_addc_u32 s93, s93, 0
	global_load_dwordx2 v[216:217], v252, s[92:93]
	s_add_u32 s92, s92, 0xa00
	s_addc_u32 s93, s93, 0
	global_load_dwordx2 v[220:221], v252, s[92:93]
	s_add_u32 s92, s92, 0xa00
	s_addc_u32 s93, s93, 0
	global_load_dwordx2 v[224:225], v252, s[92:93]
	s_add_u32 s92, s92, 0xa00
	s_addc_u32 s93, s93, 0
	global_load_dwordx2 v[228:229], v252, s[92:93]
	s_add_u32 s92, s92, 0xa00
	s_addc_u32 s93, s93, 0
	global_load_dwordx2 v[232:233], v252, s[92:93]
	s_add_u32 s92, s92, 0xa00
	s_addc_u32 s93, s93, 0
	global_load_dwordx2 v[236:237], v252, s[92:93]
	s_add_u32 s92, s92, 0xa00
	s_addc_u32 s93, s93, 0
	global_load_dwordx2 v[240:241], v252, s[92:93]
	s_add_u32 s92, s92, 0xa00
	s_addc_u32 s93, s93, 0
	global_load_dwordx2 v[244:245], v252, s[92:93]
	s_add_u32 s92, s92, 0xa00
	s_addc_u32 s93, s93, 0
	global_load_dwordx2 v[248:249], v252, s[92:93]
	s_waitcnt vmcnt(0)
	v_lshlrev_b32_e32 v210, 16, v209
	v_and_b32_e32 v211, 0xffff0000, v209
	v_and_b32_e32 v209, 0xffff0000, v208
	v_lshlrev_b32_e32 v208, 16, v208
	v_lshlrev_b32_e32 v214, 16, v213
	v_and_b32_e32 v215, 0xffff0000, v213
	v_and_b32_e32 v213, 0xffff0000, v212
	v_lshlrev_b32_e32 v212, 16, v212
	v_lshlrev_b32_e32 v218, 16, v217
	v_and_b32_e32 v219, 0xffff0000, v217
	v_and_b32_e32 v217, 0xffff0000, v216
	v_lshlrev_b32_e32 v216, 16, v216
	v_lshlrev_b32_e32 v222, 16, v221
	v_and_b32_e32 v223, 0xffff0000, v221
	v_and_b32_e32 v221, 0xffff0000, v220
	v_lshlrev_b32_e32 v220, 16, v220
	v_lshlrev_b32_e32 v226, 16, v225
	v_and_b32_e32 v227, 0xffff0000, v225
	v_and_b32_e32 v225, 0xffff0000, v224
	v_lshlrev_b32_e32 v224, 16, v224
	v_lshlrev_b32_e32 v230, 16, v229
	v_and_b32_e32 v231, 0xffff0000, v229
	v_and_b32_e32 v229, 0xffff0000, v228
	v_lshlrev_b32_e32 v228, 16, v228
	v_lshlrev_b32_e32 v234, 16, v233
	v_and_b32_e32 v235, 0xffff0000, v233
	v_and_b32_e32 v233, 0xffff0000, v232
	v_lshlrev_b32_e32 v232, 16, v232
	v_lshlrev_b32_e32 v238, 16, v237
	v_and_b32_e32 v239, 0xffff0000, v237
	v_and_b32_e32 v237, 0xffff0000, v236
	v_lshlrev_b32_e32 v236, 16, v236
	v_lshlrev_b32_e32 v242, 16, v241
	v_and_b32_e32 v243, 0xffff0000, v241
	v_and_b32_e32 v241, 0xffff0000, v240
	v_lshlrev_b32_e32 v240, 16, v240
	v_lshlrev_b32_e32 v246, 16, v245
	v_and_b32_e32 v247, 0xffff0000, v245
	v_and_b32_e32 v245, 0xffff0000, v244
	v_lshlrev_b32_e32 v244, 16, v244
	v_lshlrev_b32_e32 v250, 16, v249
	v_and_b32_e32 v251, 0xffff0000, v249
	v_and_b32_e32 v249, 0xffff0000, v248
	v_lshlrev_b32_e32 v248, 16, v248
	v_pk_fma_f32 v[208:209], v[0:1], v[208:209], v[16:17]
	v_pk_fma_f32 v[210:211], v[2:3], v[210:211], v[18:19]
	v_pk_fma_f32 v[208:209], v[4:5], v[212:213], v[208:209]
	v_pk_fma_f32 v[210:211], v[6:7], v[214:215], v[210:211]
	v_pk_fma_f32 v[208:209], v[8:9], v[216:217], v[208:209]
	v_pk_fma_f32 v[210:211], v[10:11], v[218:219], v[210:211]
	v_pk_fma_f32 v[208:209], v[12:13], v[220:221], v[208:209]
	v_pk_fma_f32 v[210:211], v[14:15], v[222:223], v[210:211]
	v_cvt_pk_bf16_f32 v208, v208, v209
	v_cvt_pk_bf16_f32 v209, v210, v211
	global_store_dwordx2 v252, v[208:209], s[94:95]
	s_add_u32 s94, s94, 0xa00
	s_addc_u32 s95, s95, 0
	v_pk_fma_f32 v[212:213], v[0:1], v[212:213], v[16:17]
	v_pk_fma_f32 v[214:215], v[2:3], v[214:215], v[18:19]
	v_pk_fma_f32 v[212:213], v[4:5], v[216:217], v[212:213]
	v_pk_fma_f32 v[214:215], v[6:7], v[218:219], v[214:215]
	v_pk_fma_f32 v[212:213], v[8:9], v[220:221], v[212:213]
	v_pk_fma_f32 v[214:215], v[10:11], v[222:223], v[214:215]
	v_pk_fma_f32 v[212:213], v[12:13], v[224:225], v[212:213]
	v_pk_fma_f32 v[214:215], v[14:15], v[226:227], v[214:215]
	v_cvt_pk_bf16_f32 v212, v212, v213
	v_cvt_pk_bf16_f32 v213, v214, v215
	global_store_dwordx2 v252, v[212:213], s[94:95]
	s_add_u32 s94, s94, 0xa00
	s_addc_u32 s95, s95, 0
	v_pk_fma_f32 v[216:217], v[0:1], v[216:217], v[16:17]
	v_pk_fma_f32 v[218:219], v[2:3], v[218:219], v[18:19]
	v_pk_fma_f32 v[216:217], v[4:5], v[220:221], v[216:217]
	v_pk_fma_f32 v[218:219], v[6:7], v[222:223], v[218:219]
	v_pk_fma_f32 v[216:217], v[8:9], v[224:225], v[216:217]
	v_pk_fma_f32 v[218:219], v[10:11], v[226:227], v[218:219]
	v_pk_fma_f32 v[216:217], v[12:13], v[228:229], v[216:217]
	v_pk_fma_f32 v[218:219], v[14:15], v[230:231], v[218:219]
	v_cvt_pk_bf16_f32 v216, v216, v217
	v_cvt_pk_bf16_f32 v217, v218, v219
	global_store_dwordx2 v252, v[216:217], s[94:95]
	s_add_u32 s94, s94, 0xa00
	s_addc_u32 s95, s95, 0
	v_pk_fma_f32 v[220:221], v[0:1], v[220:221], v[16:17]
	v_pk_fma_f32 v[222:223], v[2:3], v[222:223], v[18:19]
	v_pk_fma_f32 v[220:221], v[4:5], v[224:225], v[220:221]
	v_pk_fma_f32 v[222:223], v[6:7], v[226:227], v[222:223]
	v_pk_fma_f32 v[220:221], v[8:9], v[228:229], v[220:221]
	v_pk_fma_f32 v[222:223], v[10:11], v[230:231], v[222:223]
	v_pk_fma_f32 v[220:221], v[12:13], v[232:233], v[220:221]
	v_pk_fma_f32 v[222:223], v[14:15], v[234:235], v[222:223]
	v_cvt_pk_bf16_f32 v220, v220, v221
	v_cvt_pk_bf16_f32 v221, v222, v223
	global_store_dwordx2 v252, v[220:221], s[94:95]
	s_add_u32 s94, s94, 0xa00
	s_addc_u32 s95, s95, 0
	v_pk_fma_f32 v[224:225], v[0:1], v[224:225], v[16:17]
	v_pk_fma_f32 v[226:227], v[2:3], v[226:227], v[18:19]
	v_pk_fma_f32 v[224:225], v[4:5], v[228:229], v[224:225]
	v_pk_fma_f32 v[226:227], v[6:7], v[230:231], v[226:227]
	v_pk_fma_f32 v[224:225], v[8:9], v[232:233], v[224:225]
	v_pk_fma_f32 v[226:227], v[10:11], v[234:235], v[226:227]
	v_pk_fma_f32 v[224:225], v[12:13], v[236:237], v[224:225]
	v_pk_fma_f32 v[226:227], v[14:15], v[238:239], v[226:227]
	v_cvt_pk_bf16_f32 v224, v224, v225
	v_cvt_pk_bf16_f32 v225, v226, v227
	global_store_dwordx2 v252, v[224:225], s[94:95]
	s_add_u32 s94, s94, 0xa00
	s_addc_u32 s95, s95, 0
	v_pk_fma_f32 v[228:229], v[0:1], v[228:229], v[16:17]
	v_pk_fma_f32 v[230:231], v[2:3], v[230:231], v[18:19]
	v_pk_fma_f32 v[228:229], v[4:5], v[232:233], v[228:229]
	v_pk_fma_f32 v[230:231], v[6:7], v[234:235], v[230:231]
	v_pk_fma_f32 v[228:229], v[8:9], v[236:237], v[228:229]
	v_pk_fma_f32 v[230:231], v[10:11], v[238:239], v[230:231]
	v_pk_fma_f32 v[228:229], v[12:13], v[240:241], v[228:229]
	v_pk_fma_f32 v[230:231], v[14:15], v[242:243], v[230:231]
	v_cvt_pk_bf16_f32 v228, v228, v229
	v_cvt_pk_bf16_f32 v229, v230, v231
	global_store_dwordx2 v252, v[228:229], s[94:95]
	s_add_u32 s94, s94, 0xa00
	s_addc_u32 s95, s95, 0
	v_pk_fma_f32 v[232:233], v[0:1], v[232:233], v[16:17]
	v_pk_fma_f32 v[234:235], v[2:3], v[234:235], v[18:19]
	v_pk_fma_f32 v[232:233], v[4:5], v[236:237], v[232:233]
	v_pk_fma_f32 v[234:235], v[6:7], v[238:239], v[234:235]
	v_pk_fma_f32 v[232:233], v[8:9], v[240:241], v[232:233]
	v_pk_fma_f32 v[234:235], v[10:11], v[242:243], v[234:235]
	v_pk_fma_f32 v[232:233], v[12:13], v[244:245], v[232:233]
	v_pk_fma_f32 v[234:235], v[14:15], v[246:247], v[234:235]
	v_cvt_pk_bf16_f32 v232, v232, v233
	v_cvt_pk_bf16_f32 v233, v234, v235
	global_store_dwordx2 v252, v[232:233], s[94:95]
	s_add_u32 s94, s94, 0xa00
	s_addc_u32 s95, s95, 0
	v_pk_fma_f32 v[236:237], v[0:1], v[236:237], v[16:17]
	v_pk_fma_f32 v[238:239], v[2:3], v[238:239], v[18:19]
	v_pk_fma_f32 v[236:237], v[4:5], v[240:241], v[236:237]
	v_pk_fma_f32 v[238:239], v[6:7], v[242:243], v[238:239]
	v_pk_fma_f32 v[236:237], v[8:9], v[244:245], v[236:237]
	v_pk_fma_f32 v[238:239], v[10:11], v[246:247], v[238:239]
	v_pk_fma_f32 v[236:237], v[12:13], v[248:249], v[236:237]
	v_pk_fma_f32 v[238:239], v[14:15], v[250:251], v[238:239]
	v_cvt_pk_bf16_f32 v236, v236, v237
	v_cvt_pk_bf16_f32 v237, v238, v239
	global_store_dwordx2 v252, v[236:237], s[94:95]
	s_mov_b32 s66, 0x1a000
	s_mov_b32 s67, 0
	s_mov_b32 s68, 0x5000
	s_mov_b32 s69, 0
	v_add_u32_e32 v43, 8, v43
	v_lshl_add_u64 v[54:55], v[54:55], 0, s[66:67]
	v_lshl_add_u64 v[56:57], v[56:57], 0, s[68:69]
	s_add_u32 s84, s84, 8
	s_cmp_lt_u32 s84, s85
	s_cbranch_scc1 .Lc1_top
	s_branch .LBB0_344
